# GLU item: A-tile staging loop unrolled (all global loads in flight before the LDS writes)
# baseline (speedup 1.0000x reference)
; #define LAS __attribute__((address_space(3)))
; __device__ __forceinline__ void glu_item(Frame& F, const Args& AR, int l, int item) {
;     ...
;     bf16x8v b0[8][2];
;     wave_bfrags<K>(Bt, 0, b0, F.lane);
;     __syncthreads();
;     for (int idx = F.tid; idx < 80 * 64; idx += NTHR) { const int pc = idx & 63, row = idx >> 6;
;         v4u v = {0u, 0u, 0u, 0u}; if (row < NROW) v = *(const v4u*)(YG + (size_t)(row0 + row) * 512 + pc * 8);
;         *(LAS v4u*)(at + row * LDA + pc * 16) = v; }
.LBB0_1674:
	s_lshl_b32 s4, s13, 8
	s_and_b32 s4, s4, 0x100
	s_add_i32 s4, s4, s12
	s_ashr_i32 s5, s4, 31
	s_lshl_b64 s[6:7], s[4:5], 10
	v_lshl_add_u64 v[6:7], v[134:135], 0, s[6:7]
	v_lshl_add_u64 v[30:31], v[6:7], 0, v[194:195]
	v_mov_b32_e32 v137, v195
	v_lshl_add_u64 v[2:3], v[6:7], 0, v[136:137]
	global_load_dwordx4 v[122:125], v[30:31], off
	global_load_dwordx4 v[114:117], v[30:31], off offset:64
	global_load_dwordx4 v[126:129], v[2:3], off
	global_load_dwordx4 v[118:121], v[2:3], off offset:64
	global_load_dwordx4 v[106:109], v[30:31], off offset:128
	global_load_dwordx4 v[98:101], v[30:31], off offset:192
	global_load_dwordx4 v[110:113], v[2:3], off offset:128
	global_load_dwordx4 v[102:105], v[2:3], off offset:192
	global_load_dwordx4 v[90:93], v[30:31], off offset:256
	global_load_dwordx4 v[82:85], v[30:31], off offset:320
	global_load_dwordx4 v[94:97], v[2:3], off offset:256
	global_load_dwordx4 v[86:89], v[2:3], off offset:320
	global_load_dwordx4 v[74:77], v[30:31], off offset:384
	global_load_dwordx4 v[58:61], v[30:31], off offset:448
	global_load_dwordx4 v[78:81], v[2:3], off offset:384
	global_load_dwordx4 v[62:65], v[2:3], off offset:448
	s_lshr_b32 s5, s13, 1
	s_mulk_i32 s5, 0x44
	s_waitcnt vmcnt(0)
	s_barrier
	s_and_saveexec_b64 s[6:7], s[38:39]
	s_cbranch_execz .LBB0_1679
	v_ashrrev_i32_e32 v9, 6, v133
	v_add_u32_e32 v2, s5, v9
	v_ashrrev_i32_e32 v3, 31, v2
	v_lshlrev_b64 v[2:3], 10, v[2:3]
	v_lshl_add_u64 v[2:3], v[130:131], 0, v[2:3]
	s_mov_b64 s[8:9], 0x2000
	global_load_dwordx4 v[12:15], v[2:3], off
	v_lshl_add_u64 v[2:3], v[2:3], 0, s[8:9]
	global_load_dwordx4 v[16:19], v[2:3], off
	v_lshl_add_u64 v[2:3], v[2:3], 0, s[8:9]
	global_load_dwordx4 v[20:23], v[2:3], off
	v_lshl_add_u64 v[2:3], v[2:3], 0, s[8:9]
	global_load_dwordx4 v[24:27], v[2:3], off
	v_lshl_add_u64 v[2:3], v[2:3], 0, s[8:9]
	global_load_dwordx4 v[32:35], v[2:3], off
	v_lshl_add_u64 v[2:3], v[2:3], 0, s[8:9]
	global_load_dwordx4 v[36:39], v[2:3], off
	v_lshl_add_u64 v[2:3], v[2:3], 0, s[8:9]
	global_load_dwordx4 v[40:43], v[2:3], off
	v_lshl_add_u64 v[2:3], v[2:3], 0, s[8:9]
	global_load_dwordx4 v[44:47], v[2:3], off
	v_lshl_add_u64 v[2:3], v[2:3], 0, s[8:9]
	global_load_dwordx4 v[48:51], v[2:3], off
	v_mad_u32_u24 v10, v9, s24, v132
	v_add_u32_e32 v11, 0x10400, v10
	v_mov_b32_e32 v52, 0
	v_mov_b32_e32 v53, 0
	v_mov_b32_e32 v54, 0
	v_mov_b32_e32 v55, 0
	v_cmp_gt_u32_e32 vcc, 4, v9
	s_waitcnt vmcnt(8)
	ds_write_b128 v10, v[12:15]
	s_waitcnt vmcnt(7)
	ds_write_b128 v10, v[16:19] offset:8320
	s_waitcnt vmcnt(6)
	ds_write_b128 v10, v[20:23] offset:16640
	s_waitcnt vmcnt(5)
	ds_write_b128 v10, v[24:27] offset:24960
	s_waitcnt vmcnt(4)
	ds_write_b128 v10, v[32:35] offset:33280
	s_waitcnt vmcnt(3)
	ds_write_b128 v10, v[36:39] offset:41600
	s_waitcnt vmcnt(2)
	ds_write_b128 v10, v[40:43] offset:49920
	s_waitcnt vmcnt(1)
	ds_write_b128 v10, v[44:47] offset:58240
	s_waitcnt vmcnt(0)
	v_cndmask_b32_e32 v48, 0, v48, vcc
	v_cndmask_b32_e32 v49, 0, v49, vcc
	v_cndmask_b32_e32 v50, 0, v50, vcc
	v_cndmask_b32_e32 v51, 0, v51, vcc
	ds_write_b128 v11, v[48:51]
	ds_write_b128 v11, v[52:55] offset:8320
